# v39: + gMLP item tail: the three later gate loads issued behind the first (E2 and ATTN instances), counted waits
# speedup vs baseline: 1.0229x; 1.0029x over previous
.LBB0_1316:
	s_or_b64 exec, exec, s[0:1]
	v_or_b32_e32 v0, v18, v23
	s_xor_b64 s[0:1], s[2:3], -1
	v_add_u32_e32 v24, s54, v0
	v_readlane_b32 s2, v254, 27
	v_ashrrev_i32_e32 v25, 31, v24
	v_readlane_b32 s3, v254, 28
	v_add_u32_e32 v20, s4, v0
	v_ashrrev_i32_e32 v21, 31, v20
	v_lshl_add_u64 v[24:25], v[24:25], 2, s[2:3]
	global_load_dword v18, v[24:25], off
	v_mov_b64_e32 v[24:25], s[50:51]
	v_mad_i64_i32 v[24:25], s[2:3], v20, s84, v[24:25]
	v_readlane_b32 s2, v254, 7
	s_lshl_b32 s54, s6, 1
	v_lshlrev_b64 v[20:21], 11, v[20:21]
	v_readlane_b32 s3, v254, 8
	v_lshlrev_b32_e32 v0, 1, v19
	v_lshl_add_u64 v[24:25], v[24:25], 0, s[54:55]
	v_lshl_add_u64 v[20:21], s[2:3], 0, v[20:21]
	v_lshl_or_b32 v0, v22, 3, v0
	v_lshl_add_u64 v[26:27], v[20:21], 0, s[54:55]
	v_lshl_add_u64 v[20:21], v[24:25], 0, v[0:1]
	global_load_dwordx2 v[22:23], v[20:21], off
	global_load_dwordx2 v[120:121], v[20:21], off offset:16
	global_load_dwordx2 v[122:123], v[20:21], off offset:32
	global_load_dwordx2 v[124:125], v[20:21], off offset:48
	s_mov_b32 s5, 1
	s_mov_b64 s[2:3], 0
	s_andn2_b64 vcc, exec, s[0:1]
	s_waitcnt vmcnt(3)
	v_lshlrev_b32_e32 v24, 16, v22
	v_mul_f32_e32 v19, 0x3d372713, v24
	v_and_b32_e32 v25, 0xffff0000, v22
	v_mul_f32_e32 v19, v19, v24
	v_mov_b32_e32 v22, v24
	v_fmac_f32_e32 v22, v19, v22
	v_mul_f32_e32 v19, 0xbfcc422a, v22
	v_mul_f32_e32 v19, 0x3fb8aa3b, v19
	v_exp_f32_e32 v19, v19
	v_mov_b32_e32 v22, v25
	v_add_f32_e32 v19, 1.0, v19
	v_rcp_f32_e32 v28, v19
	v_mul_f32_e32 v19, 0x3d372713, v25
	v_mul_f32_e32 v19, v19, v25
	v_fmac_f32_e32 v22, v19, v22
	v_mul_f32_e32 v19, 0xbfcc422a, v22
	v_mul_f32_e32 v19, 0x3fb8aa3b, v19
	v_exp_f32_e32 v19, v19
	v_lshlrev_b32_e32 v22, 16, v23
	v_and_b32_e32 v23, 0xffff0000, v23
	v_add_f32_e32 v19, 1.0, v19
	v_rcp_f32_e32 v29, v19
	v_pk_add_f32 v[2:3], v[18:19], v[2:3] op_sel_hi:[0,1]
	v_mul_f32_e32 v19, 0x3d372713, v22
	v_mul_f32_e32 v19, v19, v22
	v_pk_mul_f32 v[24:25], v[28:29], v[24:25]
	s_nop 0
	v_pk_mul_f32 v[2:3], v[2:3], v[24:25]
	v_mov_b32_e32 v24, v22
	v_fmac_f32_e32 v24, v19, v24
	v_mul_f32_e32 v19, 0xbfcc422a, v24
	v_mul_f32_e32 v19, 0x3fb8aa3b, v19
	v_exp_f32_e32 v19, v19
	v_mov_b32_e32 v25, v23
	v_add_f32_e32 v19, 1.0, v19
	v_rcp_f32_e32 v24, v19
	v_mul_f32_e32 v19, 0x3d372713, v23
	v_mul_f32_e32 v19, v19, v23
	v_fmac_f32_e32 v25, v19, v25
	v_mul_f32_e32 v19, 0xbfcc422a, v25
	v_mul_f32_e32 v19, 0x3fb8aa3b, v19
	v_exp_f32_e32 v19, v19
	s_nop 0
	v_add_f32_e32 v19, 1.0, v19
	v_rcp_f32_e32 v25, v19
	v_pk_add_f32 v[4:5], v[18:19], v[4:5] op_sel_hi:[0,1]
	v_pk_add_f32 v[6:7], v[18:19], v[6:7] op_sel_hi:[0,1]
	v_pk_mul_f32 v[22:23], v[24:25], v[22:23]
	s_nop 0
	v_pk_mul_f32 v[4:5], v[4:5], v[22:23]
	v_cvt_pk_bf16_f32 v22, v2, v3
	v_cvt_pk_bf16_f32 v23, v4, v5
	v_lshl_add_u64 v[2:3], v[26:27], 0, v[0:1]
	global_store_dwordx2 v[2:3], v[22:23], off
	s_waitcnt vmcnt(3)
	v_mov_b32_e32 v4, v120
	v_mov_b32_e32 v5, v121
	v_lshlrev_b32_e32 v22, 16, v4
	v_mul_f32_e32 v0, 0x3d372713, v22
	v_and_b32_e32 v23, 0xffff0000, v4
	v_mul_f32_e32 v0, v0, v22
	v_mov_b32_e32 v4, v22
	v_fmac_f32_e32 v4, v0, v4
	v_mul_f32_e32 v0, 0xbfcc422a, v4
	v_mul_f32_e32 v0, 0x3fb8aa3b, v0
	v_exp_f32_e32 v0, v0
	v_mov_b32_e32 v4, v23
	v_add_f32_e32 v0, 1.0, v0
	v_rcp_f32_e32 v24, v0
	v_mul_f32_e32 v0, 0x3d372713, v23
	v_mul_f32_e32 v0, v0, v23
	v_fmac_f32_e32 v4, v0, v4
	v_mul_f32_e32 v0, 0xbfcc422a, v4
	v_mul_f32_e32 v0, 0x3fb8aa3b, v0
	v_exp_f32_e32 v0, v0
	v_lshlrev_b32_e32 v4, 16, v5
	v_mov_b32_e32 v19, v4
	v_and_b32_e32 v5, 0xffff0000, v5
	v_add_f32_e32 v0, 1.0, v0
	v_rcp_f32_e32 v25, v0
	v_mul_f32_e32 v0, 0x3d372713, v4
	v_mul_f32_e32 v0, v0, v4
	v_fmac_f32_e32 v19, v0, v19
	v_mul_f32_e32 v0, 0xbfcc422a, v19
	v_mul_f32_e32 v0, 0x3fb8aa3b, v0
	v_exp_f32_e32 v0, v0
	v_pk_mul_f32 v[22:23], v[24:25], v[22:23]
	v_mov_b32_e32 v19, v5
	v_pk_mul_f32 v[6:7], v[6:7], v[22:23]
	v_add_f32_e32 v0, 1.0, v0
	v_rcp_f32_e32 v22, v0
	v_mul_f32_e32 v0, 0x3d372713, v5
	v_mul_f32_e32 v0, v0, v5
	v_fmac_f32_e32 v19, v0, v19
	v_mul_f32_e32 v0, 0xbfcc422a, v19
	v_mul_f32_e32 v0, 0x3fb8aa3b, v0
	v_exp_f32_e32 v0, v0
	v_pk_add_f32 v[8:9], v[18:19], v[8:9] op_sel_hi:[0,1]
	v_cvt_pk_bf16_f32 v6, v6, v7
	v_add_f32_e32 v0, 1.0, v0
	v_rcp_f32_e32 v23, v0
	s_nop 0
	v_pk_mul_f32 v[4:5], v[22:23], v[4:5]
	s_nop 0
	v_pk_mul_f32 v[4:5], v[8:9], v[4:5]
	s_nop 0
	v_cvt_pk_bf16_f32 v7, v4, v5
	s_nop 0
	global_store_dwordx2 v[2:3], v[6:7], off offset:16
	s_waitcnt vmcnt(3)
	v_mov_b32_e32 v4, v122
	v_mov_b32_e32 v5, v123
	v_lshlrev_b32_e32 v6, 16, v4
	v_mul_f32_e32 v0, 0x3d372713, v6
	v_and_b32_e32 v7, 0xffff0000, v4
	v_mul_f32_e32 v0, v0, v6
	v_mov_b32_e32 v4, v6
	v_fmac_f32_e32 v4, v0, v4
	v_mul_f32_e32 v0, 0xbfcc422a, v4
	v_mul_f32_e32 v0, 0x3fb8aa3b, v0
	v_exp_f32_e32 v0, v0
	v_mov_b32_e32 v4, v7
	v_add_f32_e32 v0, 1.0, v0
	v_rcp_f32_e32 v8, v0
	v_mul_f32_e32 v0, 0x3d372713, v7
	v_mul_f32_e32 v0, v0, v7
	v_fmac_f32_e32 v4, v0, v4
	v_mul_f32_e32 v0, 0xbfcc422a, v4
	v_mul_f32_e32 v0, 0x3fb8aa3b, v0
	v_exp_f32_e32 v0, v0
	v_lshlrev_b32_e32 v4, 16, v5
	v_and_b32_e32 v5, 0xffff0000, v5
	v_add_f32_e32 v0, 1.0, v0
	v_rcp_f32_e32 v9, v0
	v_mul_f32_e32 v0, 0x3d372713, v4
	v_mul_f32_e32 v0, v0, v4
	v_pk_mul_f32 v[6:7], v[8:9], v[6:7]
	v_pk_add_f32 v[8:9], v[18:19], v[10:11] op_sel_hi:[0,1]
	v_pk_mul_f32 v[6:7], v[8:9], v[6:7]
	v_mov_b32_e32 v8, v4
	v_fmac_f32_e32 v8, v0, v8
	v_mul_f32_e32 v0, 0xbfcc422a, v8
	v_mul_f32_e32 v0, 0x3fb8aa3b, v0
	v_exp_f32_e32 v0, v0
	v_mov_b32_e32 v9, v5
	v_cvt_pk_bf16_f32 v6, v6, v7
	v_add_f32_e32 v0, 1.0, v0
	v_rcp_f32_e32 v8, v0
	v_mul_f32_e32 v0, 0x3d372713, v5
	v_mul_f32_e32 v0, v0, v5
	v_fmac_f32_e32 v9, v0, v9
	v_mul_f32_e32 v0, 0xbfcc422a, v9
	v_mul_f32_e32 v0, 0x3fb8aa3b, v0
	v_exp_f32_e32 v0, v0
	s_nop 0
	v_add_f32_e32 v0, 1.0, v0
	v_rcp_f32_e32 v9, v0
	s_nop 0
	v_pk_mul_f32 v[4:5], v[8:9], v[4:5]
	v_pk_add_f32 v[8:9], v[18:19], v[12:13] op_sel_hi:[0,1]
	v_pk_mul_f32 v[4:5], v[8:9], v[4:5]
	s_nop 0
	v_cvt_pk_bf16_f32 v7, v4, v5
	s_nop 0
	global_store_dwordx2 v[2:3], v[6:7], off offset:32
	s_waitcnt vmcnt(3)
	v_mov_b32_e32 v4, v124
	v_mov_b32_e32 v5, v125
	v_lshlrev_b32_e32 v6, 16, v4
	v_mul_f32_e32 v0, 0x3d372713, v6
	v_and_b32_e32 v7, 0xffff0000, v4
	v_mul_f32_e32 v0, v0, v6
	v_mov_b32_e32 v4, v6
	v_fmac_f32_e32 v4, v0, v4
	v_mul_f32_e32 v0, 0xbfcc422a, v4
	v_mul_f32_e32 v0, 0x3fb8aa3b, v0
	v_exp_f32_e32 v0, v0
	v_mov_b32_e32 v4, v7
	v_add_f32_e32 v0, 1.0, v0
	v_rcp_f32_e32 v8, v0
	v_mul_f32_e32 v0, 0x3d372713, v7
	v_mul_f32_e32 v0, v0, v7
	v_fmac_f32_e32 v4, v0, v4
	v_mul_f32_e32 v0, 0xbfcc422a, v4
	v_mul_f32_e32 v0, 0x3fb8aa3b, v0
	v_exp_f32_e32 v0, v0
	v_lshlrev_b32_e32 v4, 16, v5
	v_and_b32_e32 v5, 0xffff0000, v5
	v_add_f32_e32 v0, 1.0, v0
	v_rcp_f32_e32 v9, v0
	v_mul_f32_e32 v0, 0x3d372713, v4
	v_mul_f32_e32 v0, v0, v4
	v_pk_mul_f32 v[6:7], v[8:9], v[6:7]
	v_pk_add_f32 v[8:9], v[18:19], v[14:15] op_sel_hi:[0,1]
	v_pk_mul_f32 v[6:7], v[8:9], v[6:7]
	v_mov_b32_e32 v8, v4
	v_fmac_f32_e32 v8, v0, v8
	v_mul_f32_e32 v0, 0xbfcc422a, v8
	v_mul_f32_e32 v0, 0x3fb8aa3b, v0
	v_exp_f32_e32 v0, v0
	v_mov_b32_e32 v9, v5
	v_cvt_pk_bf16_f32 v6, v6, v7
	v_add_f32_e32 v0, 1.0, v0
	v_rcp_f32_e32 v8, v0
	v_mul_f32_e32 v0, 0x3d372713, v5
	v_mul_f32_e32 v0, v0, v5
	v_fmac_f32_e32 v9, v0, v9
	v_mul_f32_e32 v0, 0xbfcc422a, v9
	v_mul_f32_e32 v0, 0x3fb8aa3b, v0
	v_exp_f32_e32 v0, v0
	s_nop 0
	v_add_f32_e32 v0, 1.0, v0
	v_rcp_f32_e32 v9, v0
	s_nop 0
	v_pk_mul_f32 v[4:5], v[8:9], v[4:5]
	v_pk_add_f32 v[8:9], v[18:19], v[16:17] op_sel_hi:[0,1]
	v_pk_mul_f32 v[4:5], v[8:9], v[4:5]
	s_nop 0
	v_cvt_pk_bf16_f32 v7, v4, v5
	global_store_dwordx2 v[2:3], v[6:7], off offset:48
	s_barrier
	s_cbranch_vccz .LBB0_1333

.LBB0_1491:
	s_or_b64 exec, exec, s[4:5]
	v_add_u32_e32 v24, s2, v18
	v_readlane_b32 s2, v254, 27
	v_ashrrev_i32_e32 v25, 31, v24
	v_readlane_b32 s3, v254, 28
	v_add_u32_e32 v20, s6, v18
	v_lshlrev_b32_e32 v18, 1, v19
	v_lshl_add_u64 v[24:25], v[24:25], 2, s[2:3]
	global_load_dword v0, v[24:25], off
	v_mad_i64_i32 v[24:25], s[2:3], v20, s84, 0
	v_lshl_or_b32 v28, v22, 3, v18
	s_add_u32 s2, s14, s0
	v_or_b32_e32 v24, v24, v28
	s_addc_u32 s3, s15, s1
	v_lshl_add_u64 v[18:19], s[2:3], 0, v[24:25]
	v_add_co_u32_e32 v18, vcc, s75, v18
	v_ashrrev_i32_e32 v21, 31, v20
	s_nop 0
	v_addc_co_u32_e32 v19, vcc, 0, v19, vcc
	global_load_dwordx2 v[22:23], v[18:19], off
	global_load_dwordx2 v[114:115], v[18:19], off offset:16
	global_load_dwordx2 v[116:117], v[18:19], off offset:32
	global_load_dwordx2 v[118:119], v[18:19], off offset:48
	v_lshlrev_b64 v[20:21], 11, v[20:21]
	v_or_b32_e32 v20, v20, v28
	s_add_u32 s0, s0, 0x80
	s_addc_u32 s1, 0, s1
	s_cmpk_eq_i32 s0, 0x200
	s_waitcnt vmcnt(4)
	v_pk_add_f32 v[2:3], v[0:1], v[2:3] op_sel_hi:[0,1]
	v_pk_add_f32 v[4:5], v[0:1], v[4:5] op_sel_hi:[0,1]
	v_pk_add_f32 v[6:7], v[0:1], v[6:7] op_sel_hi:[0,1]
	v_pk_add_f32 v[8:9], v[0:1], v[8:9] op_sel_hi:[0,1]
	s_waitcnt vmcnt(3)
	v_lshlrev_b32_e32 v24, 16, v22
	v_and_b32_e32 v25, 0xffff0000, v22
	v_mul_f32_e32 v22, 0x3d372713, v24
	v_mul_f32_e32 v22, v22, v24
	v_mov_b32_e32 v26, v24
	v_fmac_f32_e32 v26, v22, v26
	v_mul_f32_e32 v22, 0xbfcc422a, v26
	v_mul_f32_e32 v22, 0x3fb8aa3b, v22
	v_exp_f32_e32 v22, v22
	v_mov_b32_e32 v27, v25
	v_add_f32_e32 v22, 1.0, v22
	v_rcp_f32_e32 v26, v22
	v_mul_f32_e32 v22, 0x3d372713, v25
	v_mul_f32_e32 v22, v22, v25
	v_fmac_f32_e32 v27, v22, v27
	v_mul_f32_e32 v22, 0xbfcc422a, v27
	v_mul_f32_e32 v22, 0x3fb8aa3b, v22
	v_exp_f32_e32 v22, v22
	s_nop 0
	v_add_f32_e32 v22, 1.0, v22
	v_rcp_f32_e32 v27, v22
	v_lshlrev_b32_e32 v22, 16, v23
	v_and_b32_e32 v23, 0xffff0000, v23
	v_pk_mul_f32 v[24:25], v[26:27], v[24:25]
	s_nop 0
	v_pk_mul_f32 v[2:3], v[2:3], v[24:25]
	v_mul_f32_e32 v24, 0x3d372713, v22
	v_mul_f32_e32 v24, v24, v22
	v_mov_b32_e32 v25, v22
	v_fmac_f32_e32 v25, v24, v25
	v_mul_f32_e32 v24, 0xbfcc422a, v25
	v_mul_f32_e32 v25, 0x3d372713, v23
	v_mul_f32_e32 v25, v25, v23
	v_mov_b32_e32 v26, v23
	v_fmac_f32_e32 v26, v25, v26
	v_mul_f32_e32 v25, 0xbfcc422a, v26
	v_mul_f32_e32 v24, 0x3fb8aa3b, v24
	v_mul_f32_e32 v25, 0x3fb8aa3b, v25
	v_exp_f32_e32 v24, v24
	v_exp_f32_e32 v25, v25
	v_add_f32_e32 v24, 1.0, v24
	v_add_f32_e32 v25, 1.0, v25
	v_rcp_f32_e32 v24, v24
	v_rcp_f32_e32 v25, v25
	s_nop 0
	v_pk_mul_f32 v[22:23], v[24:25], v[22:23]
	s_nop 0
	v_pk_mul_f32 v[22:23], v[4:5], v[22:23]
	v_cvt_pk_bf16_f32 v4, v2, v3
	v_lshl_add_u64 v[2:3], s[2:3], 0, v[20:21]
	s_mov_b32 s2, 0x13900000
	v_add_co_u32_e32 v2, vcc, s2, v2
	v_cvt_pk_bf16_f32 v5, v22, v23
	s_nop 0
	v_addc_co_u32_e32 v3, vcc, 0, v3, vcc
	global_store_dwordx2 v[2:3], v[4:5], off
	s_waitcnt vmcnt(3)
	v_mov_b32_e32 v20, v114
	v_mov_b32_e32 v21, v115
	v_lshlrev_b32_e32 v4, 16, v20
	v_and_b32_e32 v5, 0xffff0000, v20
	v_mul_f32_e32 v20, 0x3d372713, v4
	v_mul_f32_e32 v20, v20, v4
	v_mov_b32_e32 v22, v4
	v_fmac_f32_e32 v22, v20, v22
	v_mul_f32_e32 v20, 0xbfcc422a, v22
	v_mul_f32_e32 v20, 0x3fb8aa3b, v20
	v_exp_f32_e32 v20, v20
	v_mov_b32_e32 v23, v5
	v_add_f32_e32 v20, 1.0, v20
	v_rcp_f32_e32 v22, v20
	v_mul_f32_e32 v20, 0x3d372713, v5
	v_mul_f32_e32 v20, v20, v5
	v_fmac_f32_e32 v23, v20, v23
	v_mul_f32_e32 v20, 0xbfcc422a, v23
	v_mul_f32_e32 v20, 0x3fb8aa3b, v20
	v_exp_f32_e32 v20, v20
	s_nop 0
	v_add_f32_e32 v20, 1.0, v20
	v_rcp_f32_e32 v23, v20
	s_nop 0
	v_pk_mul_f32 v[4:5], v[22:23], v[4:5]
	s_nop 0
	v_pk_mul_f32 v[4:5], v[6:7], v[4:5]
	v_lshlrev_b32_e32 v6, 16, v21
	v_mul_f32_e32 v20, 0x3d372713, v6
	v_and_b32_e32 v7, 0xffff0000, v21
	v_mul_f32_e32 v20, v20, v6
	v_mov_b32_e32 v21, v6
	v_fmac_f32_e32 v21, v20, v21
	v_mul_f32_e32 v20, 0xbfcc422a, v21
	v_mul_f32_e32 v21, 0x3d372713, v7
	v_mul_f32_e32 v21, v21, v7
	v_mov_b32_e32 v22, v7
	v_fmac_f32_e32 v22, v21, v22
	v_mul_f32_e32 v21, 0xbfcc422a, v22
	v_mul_f32_e32 v20, 0x3fb8aa3b, v20
	v_mul_f32_e32 v21, 0x3fb8aa3b, v21
	v_exp_f32_e32 v20, v20
	v_exp_f32_e32 v21, v21
	v_cvt_pk_bf16_f32 v4, v4, v5
	v_add_f32_e32 v20, 1.0, v20
	v_add_f32_e32 v21, 1.0, v21
	v_rcp_f32_e32 v20, v20
	v_rcp_f32_e32 v21, v21
	s_nop 0
	v_pk_mul_f32 v[6:7], v[20:21], v[6:7]
	s_nop 0
	v_pk_mul_f32 v[6:7], v[8:9], v[6:7]
	s_nop 0
	v_cvt_pk_bf16_f32 v5, v6, v7
	global_store_dwordx2 v[2:3], v[4:5], off offset:16
	s_waitcnt vmcnt(3)
	v_mov_b32_e32 v6, v116
	v_mov_b32_e32 v7, v117
	v_lshlrev_b32_e32 v4, 16, v6
	v_and_b32_e32 v5, 0xffff0000, v6
	v_mul_f32_e32 v6, 0x3d372713, v4
	v_mul_f32_e32 v6, v6, v4
	v_mov_b32_e32 v8, v4
	v_fmac_f32_e32 v8, v6, v8
	v_mul_f32_e32 v6, 0xbfcc422a, v8
	v_mul_f32_e32 v6, 0x3fb8aa3b, v6
	v_exp_f32_e32 v6, v6
	v_mov_b32_e32 v9, v5
	v_add_f32_e32 v6, 1.0, v6
	v_rcp_f32_e32 v8, v6
	v_mul_f32_e32 v6, 0x3d372713, v5
	v_mul_f32_e32 v6, v6, v5
	v_fmac_f32_e32 v9, v6, v9
	v_mul_f32_e32 v6, 0xbfcc422a, v9
	v_mul_f32_e32 v6, 0x3fb8aa3b, v6
	v_exp_f32_e32 v6, v6
	s_nop 0
	v_add_f32_e32 v6, 1.0, v6
	v_rcp_f32_e32 v9, v6
	v_lshlrev_b32_e32 v6, 16, v7
	v_and_b32_e32 v7, 0xffff0000, v7
	v_pk_mul_f32 v[4:5], v[8:9], v[4:5]
	v_pk_add_f32 v[8:9], v[0:1], v[10:11] op_sel_hi:[0,1]
	v_pk_mul_f32 v[4:5], v[8:9], v[4:5]
	v_mul_f32_e32 v8, 0x3d372713, v6
	v_mul_f32_e32 v8, v8, v6
	v_mov_b32_e32 v9, v6
	v_fmac_f32_e32 v9, v8, v9
	v_mul_f32_e32 v8, 0xbfcc422a, v9
	v_mul_f32_e32 v9, 0x3d372713, v7
	v_mul_f32_e32 v9, v9, v7
	v_mov_b32_e32 v10, v7
	v_fmac_f32_e32 v10, v9, v10
	v_mul_f32_e32 v9, 0xbfcc422a, v10
	v_mul_f32_e32 v8, 0x3fb8aa3b, v8
	v_mul_f32_e32 v9, 0x3fb8aa3b, v9
	v_exp_f32_e32 v8, v8
	v_exp_f32_e32 v9, v9
	v_cvt_pk_bf16_f32 v4, v4, v5
	v_add_f32_e32 v8, 1.0, v8
	v_add_f32_e32 v9, 1.0, v9
	v_rcp_f32_e32 v8, v8
	v_rcp_f32_e32 v9, v9
	s_nop 0
	v_pk_mul_f32 v[6:7], v[8:9], v[6:7]
	v_pk_add_f32 v[8:9], v[0:1], v[12:13] op_sel_hi:[0,1]
	v_pk_mul_f32 v[6:7], v[8:9], v[6:7]
	s_nop 0
	v_cvt_pk_bf16_f32 v5, v6, v7
	global_store_dwordx2 v[2:3], v[4:5], off offset:32
	s_waitcnt vmcnt(3)
	v_mov_b32_e32 v4, v118
	v_mov_b32_e32 v5, v119
	v_lshlrev_b32_e32 v6, 16, v4
	v_and_b32_e32 v7, 0xffff0000, v4
	v_mul_f32_e32 v4, 0x3d372713, v6
	v_mul_f32_e32 v4, v4, v6
	v_mov_b32_e32 v8, v6
	v_fmac_f32_e32 v8, v4, v8
	v_mul_f32_e32 v4, 0xbfcc422a, v8
	v_mul_f32_e32 v4, 0x3fb8aa3b, v4
	v_exp_f32_e32 v4, v4
	v_mov_b32_e32 v9, v7
	v_add_f32_e32 v4, 1.0, v4
	v_rcp_f32_e32 v8, v4
	v_mul_f32_e32 v4, 0x3d372713, v7
	v_mul_f32_e32 v4, v4, v7
	v_fmac_f32_e32 v9, v4, v9
	v_mul_f32_e32 v4, 0xbfcc422a, v9
	v_mul_f32_e32 v4, 0x3fb8aa3b, v4
	v_exp_f32_e32 v4, v4
	s_nop 0
	v_add_f32_e32 v4, 1.0, v4
	v_rcp_f32_e32 v9, v4
	v_lshlrev_b32_e32 v4, 16, v5
	v_and_b32_e32 v5, 0xffff0000, v5
	v_mov_b32_e32 v10, v5
	v_pk_mul_f32 v[6:7], v[8:9], v[6:7]
	v_pk_add_f32 v[8:9], v[0:1], v[14:15] op_sel_hi:[0,1]
	v_pk_mul_f32 v[6:7], v[8:9], v[6:7]
	v_mul_f32_e32 v8, 0x3d372713, v4
	v_mul_f32_e32 v8, v8, v4
	v_mov_b32_e32 v9, v4
	v_fmac_f32_e32 v9, v8, v9
	v_mul_f32_e32 v8, 0xbfcc422a, v9
	v_mul_f32_e32 v9, 0x3d372713, v5
	v_mul_f32_e32 v9, v9, v5
	v_fmac_f32_e32 v10, v9, v10
	v_mul_f32_e32 v9, 0xbfcc422a, v10
	v_mul_f32_e32 v8, 0x3fb8aa3b, v8
	v_mul_f32_e32 v9, 0x3fb8aa3b, v9
	v_exp_f32_e32 v8, v8
	v_exp_f32_e32 v9, v9
	v_cvt_pk_bf16_f32 v6, v6, v7
	v_add_f32_e32 v8, 1.0, v8
	v_add_f32_e32 v9, 1.0, v9
	v_rcp_f32_e32 v8, v8
	v_rcp_f32_e32 v9, v9
	s_nop 0
	v_pk_mul_f32 v[4:5], v[8:9], v[4:5]
	v_pk_add_f32 v[8:9], v[0:1], v[16:17] op_sel_hi:[0,1]
	v_pk_mul_f32 v[4:5], v[8:9], v[4:5]
	s_nop 0
	v_cvt_pk_bf16_f32 v7, v4, v5
	global_store_dwordx2 v[2:3], v[6:7], off offset:48
	s_barrier
	s_cbranch_scc1 .LBB0_1508
